# FoX tile loop: wave-uniform diagonal test shortened to one s_cbranch_scc0 (loop-edge edit, docs 7.12)
# baseline (speedup 1.0000x reference)
.LBB0_251:
	s_or_b32 s34, s12, s20
	s_cmp_gt_i32 s34, s18
	s_cbranch_scc1 .LBB0_250
	s_or_b32 s12, s12, s21
	s_mul_i32 s13, s12, 0x3000
	v_add_u32_e32 v52, s13, v140
	ds_read_b128 v[48:51], v52
	ds_read_b128 v[96:99], v52 offset:512
	ds_read_b128 v[100:103], v52 offset:2048
	ds_read_b128 v[104:107], v52 offset:2560
	ds_read_b128 v[108:111], v52 offset:4096
	ds_read_b128 v[112:115], v52 offset:4608
	ds_read_b128 v[116:119], v52 offset:6144
	ds_read_b128 v[120:123], v52 offset:6656
	s_waitcnt lgkmcnt(7)
	v_mfma_f32_32x32x16_bf16 v[64:79], v[48:51], v[80:83], v[32:47]
	s_waitcnt lgkmcnt(6)
	v_mfma_f32_32x32x16_bf16 v[48:63], v[96:99], v[80:83], v[32:47]
	s_waitcnt lgkmcnt(5)
	v_mfma_f32_32x32x16_bf16 v[64:79], v[100:103], v[84:87], v[64:79]
	s_waitcnt lgkmcnt(4)
	v_mfma_f32_32x32x16_bf16 v[48:63], v[104:107], v[84:87], v[48:63]
	s_waitcnt lgkmcnt(3)
	v_mfma_f32_32x32x16_bf16 v[64:79], v[108:111], v[88:91], v[64:79]
	s_waitcnt lgkmcnt(2)
	v_mfma_f32_32x32x16_bf16 v[48:63], v[112:115], v[88:91], v[48:63]
	s_waitcnt lgkmcnt(1)
	v_mfma_f32_32x32x16_bf16 v[64:79], v[116:119], v[92:95], v[64:79]
	s_waitcnt lgkmcnt(0)
	v_mfma_f32_32x32x16_bf16 v[48:63], v[120:123], v[92:95], v[48:63]
	v_lshl_add_u32 v102, s12, 13, v142
	ds_read_b64_tr_b16 v[124:125], v102 offset:49152
	ds_read_b64_tr_b16 v[126:127], v102 offset:49664
	ds_read_b64_tr_b16 v[120:121], v102 offset:50176
	ds_read_b64_tr_b16 v[122:123], v102 offset:50688
	ds_read_b64_tr_b16 v[116:117], v102 offset:53248
	ds_read_b64_tr_b16 v[118:119], v102 offset:53760
	ds_read_b64_tr_b16 v[112:113], v102 offset:54272
	ds_read_b64_tr_b16 v[114:115], v102 offset:54784
	ds_read_b64_tr_b16 v[108:109], v102 offset:51200
	ds_read_b64_tr_b16 v[110:111], v102 offset:51712
	ds_read_b64_tr_b16 v[96:97], v102 offset:52224
	ds_read_b64_tr_b16 v[98:99], v102 offset:52736
	ds_read_b64_tr_b16 v[104:105], v102 offset:55296
	ds_read_b64_tr_b16 v[106:107], v102 offset:55808
	ds_read_b64_tr_b16 v[100:101], v102 offset:56320
	ds_read_b64_tr_b16 v[102:103], v102 offset:56832
	v_lshl_add_u32 v161, s12, 10, v141
	ds_read_b128 v[144:147], v161
	ds_read_b128 v[148:151], v161 offset:128
	ds_read_b128 v[152:155], v161 offset:32
	ds_read_b128 v[156:159], v161 offset:160
	s_cmp_eq_u32 s34, s18
	s_waitcnt lgkmcnt(3)
	v_pk_add_f32 v[138:139], v[64:65], v[144:145] neg_lo:[0,1] neg_hi:[0,1]
	s_waitcnt lgkmcnt(2)
	v_pk_add_f32 v[64:65], v[48:49], v[148:149] neg_lo:[0,1] neg_hi:[0,1]
	v_pk_add_f32 v[136:137], v[66:67], v[146:147] neg_lo:[0,1] neg_hi:[0,1]
	v_pk_add_f32 v[48:49], v[50:51], v[150:151] neg_lo:[0,1] neg_hi:[0,1]
	s_waitcnt lgkmcnt(1)
	v_pk_add_f32 v[68:69], v[68:69], v[152:153] neg_lo:[0,1] neg_hi:[0,1]
	s_waitcnt lgkmcnt(0)
	v_pk_add_f32 v[50:51], v[52:53], v[156:157] neg_lo:[0,1] neg_hi:[0,1]
	ds_read_b128 v[144:147], v161 offset:64
	v_pk_add_f32 v[70:71], v[70:71], v[154:155] neg_lo:[0,1] neg_hi:[0,1]
	ds_read_b128 v[148:151], v161 offset:192
	v_pk_add_f32 v[66:67], v[54:55], v[158:159] neg_lo:[0,1] neg_hi:[0,1]
	ds_read_b128 v[152:155], v161 offset:96
	ds_read_b128 v[156:159], v161 offset:224
	s_waitcnt lgkmcnt(3)
	v_pk_add_f32 v[72:73], v[72:73], v[144:145] neg_lo:[0,1] neg_hi:[0,1]
	s_waitcnt lgkmcnt(2)
	v_pk_add_f32 v[54:55], v[56:57], v[148:149] neg_lo:[0,1] neg_hi:[0,1]
	v_pk_add_f32 v[74:75], v[74:75], v[146:147] neg_lo:[0,1] neg_hi:[0,1]
	v_pk_add_f32 v[52:53], v[58:59], v[150:151] neg_lo:[0,1] neg_hi:[0,1]
	s_waitcnt lgkmcnt(1)
	v_pk_add_f32 v[76:77], v[76:77], v[152:153] neg_lo:[0,1] neg_hi:[0,1]
	s_waitcnt lgkmcnt(0)
	v_pk_add_f32 v[56:57], v[60:61], v[156:157] neg_lo:[0,1] neg_hi:[0,1]
	v_pk_add_f32 v[60:61], v[78:79], v[154:155] neg_lo:[0,1] neg_hi:[0,1]
	v_pk_add_f32 v[58:59], v[62:63], v[158:159] neg_lo:[0,1] neg_hi:[0,1]
	s_cbranch_scc0 .LBB0_256
	v_cndmask_b32_e64 v138, v138, v229, s[42:43]
	v_cndmask_b32_e64 v139, v229, v139, s[44:45]
	v_cndmask_b32_e64 v136, v136, v229, s[48:49]
	v_cndmask_b32_e64 v137, v137, v229, s[46:47]
	v_cndmask_b32_e64 v68, v68, v229, s[52:53]
	v_cndmask_b32_e64 v69, v69, v229, s[50:51]
	v_cndmask_b32_e64 v70, v70, v229, s[56:57]
	v_cndmask_b32_e64 v71, v71, v229, s[54:55]
	v_cndmask_b32_e64 v72, v72, v229, s[60:61]
	v_cndmask_b32_e64 v73, v73, v229, s[58:59]
	v_cndmask_b32_e64 v74, v74, v229, s[64:65]
	v_cndmask_b32_e64 v75, v75, v229, s[62:63]
	v_cndmask_b32_e64 v76, v76, v229, s[68:69]
	v_cndmask_b32_e64 v77, v77, v229, s[66:67]
	v_cndmask_b32_e64 v61, v61, v229, s[70:71]
	v_cndmask_b32_e64 v60, v60, v229, s[72:73]
	v_cndmask_b32_e64 v64, v64, v229, s[6:7]
	v_cndmask_b32_e64 v65, v65, v229, s[4:5]
	v_cndmask_b32_e64 v48, v48, v229, s[38:39]
	v_cndmask_b32_e64 v49, v49, v229, s[98:99]
	v_cndmask_b32_e64 v50, v50, v229, s[96:97]
	v_cndmask_b32_e64 v51, v51, v229, s[94:95]
	v_cndmask_b32_e64 v66, v66, v229, s[92:93]
	v_cndmask_b32_e64 v67, v67, v229, s[90:91]
	v_cndmask_b32_e64 v54, v54, v229, s[88:89]
	v_cndmask_b32_e64 v55, v55, v229, s[86:87]
	v_cndmask_b32_e64 v52, v52, v229, s[84:85]
	v_cndmask_b32_e64 v53, v53, v229, s[82:83]
	v_cndmask_b32_e64 v56, v56, v229, s[80:81]
	v_cndmask_b32_e64 v57, v57, v229, s[78:79]
	v_cndmask_b32_e64 v58, v58, v229, s[76:77]
	v_cndmask_b32_e64 v59, v59, v229, s[74:75]
